# per-loop choice of the prioritised half: waves 0-3 in ff-in/ff1/ff2 main loops, waves 4-7 in the single-tile phases (branch-merge, w_out, PLE gate)
# baseline (speedup 1.0000x reference)
; template <class Epi, bool SEQ>
; DEV void gemm_phase(PG8_LAS unsigned char* lds, const Gemm g, const Epi& E) {
;     ...
;     const bool has_next = next_unit<SEQ>(g, ui + 1, G, cblk, nxt);
;     const char* nA = has_next ? PG8_ABASE(nxt) : cA; const char* nB = has_next ? PG8_BBASE(nxt) : cB;
;     ...
;     if (!keep) {
; #pragma unroll
;       for (int a = 0; a < 2; ++a)
; #pragma unroll
;         for (int b = 0; b < 2; ++b)
; #pragma unroll
;           for (int m = 0; m < 4; ++m)
; #pragma unroll
;             for (int n = 0; n < 2; ++n) acc[a][b][m][n] = (f32x4){0.f, 0.f, 0.f, 0.f};
;     }
;     cur = nxt; cA = nA; cB = nB; ++ui;
.LBB0_129:
	s_ashr_i32 s39, s38, 31
	s_lshl_b64 s[8:9], s[38:39], 19
	s_add_u32 s64, s24, s8
	s_addc_u32 s65, s25, s9
	s_and_b64 s[8:9], s[62:63], exec
	s_cselect_b32 s39, s65, s3
	s_cselect_b32 s43, s64, s2
	s_ashr_i32 s61, s60, 31
	s_lshl_b64 s[8:9], s[60:61], 19
	s_add_u32 s66, s0, s8
	s_addc_u32 s67, s1, s9
	s_and_b64 s[8:9], s[62:63], exec
	s_cselect_b32 s44, s67, s5
	s_cselect_b32 s45, s66, s4
	s_add_u32 s2, s2, 0x40080
	s_addc_u32 s3, s3, 0
	s_add_u32 s46, s4, 0x100
	v_mov_b32_e32 v0, 0
	s_addc_u32 s47, s5, 0
	s_mov_b32 s48, -2
	v_mov_b32_e32 v1, v0
	v_mov_b32_e32 v2, v0
	v_mov_b32_e32 v3, v0
	v_mov_b32_e32 v4, v0
	v_mov_b32_e32 v5, v0
	v_mov_b32_e32 v6, v0
	v_mov_b32_e32 v7, v0
	v_mov_b32_e32 v16, v0
	v_mov_b32_e32 v17, v0
	v_mov_b32_e32 v18, v0
	v_mov_b32_e32 v19, v0
	v_mov_b32_e32 v20, v0
	v_mov_b32_e32 v21, v0
	v_mov_b32_e32 v22, v0
	v_mov_b32_e32 v23, v0
	v_mov_b32_e32 v32, v0
	v_mov_b32_e32 v33, v0
	v_mov_b32_e32 v34, v0
	v_mov_b32_e32 v35, v0
	v_mov_b32_e32 v36, v0
	v_mov_b32_e32 v37, v0
	v_mov_b32_e32 v38, v0
	v_mov_b32_e32 v39, v0
	v_mov_b32_e32 v48, v0
	v_mov_b32_e32 v49, v0
	v_mov_b32_e32 v50, v0
	v_mov_b32_e32 v51, v0
	v_mov_b32_e32 v52, v0
	v_mov_b32_e32 v53, v0
	v_mov_b32_e32 v54, v0
	v_mov_b32_e32 v55, v0
	v_mov_b32_e32 v8, v0
	v_mov_b32_e32 v9, v0
	v_mov_b32_e32 v10, v0
	v_mov_b32_e32 v11, v0
	v_mov_b32_e32 v12, v0
	v_mov_b32_e32 v13, v0
	v_mov_b32_e32 v14, v0
	v_mov_b32_e32 v15, v0
	v_mov_b32_e32 v24, v0
	v_mov_b32_e32 v25, v0
	v_mov_b32_e32 v26, v0
	v_mov_b32_e32 v27, v0
	v_mov_b32_e32 v28, v0
	v_mov_b32_e32 v29, v0
	v_mov_b32_e32 v30, v0
	v_mov_b32_e32 v31, v0
	v_mov_b32_e32 v40, v0
	v_mov_b32_e32 v41, v0
	v_mov_b32_e32 v42, v0
	v_mov_b32_e32 v43, v0
	v_mov_b32_e32 v44, v0
	v_mov_b32_e32 v45, v0
	v_mov_b32_e32 v46, v0
	v_mov_b32_e32 v47, v0
	v_mov_b32_e32 v56, v0
	v_mov_b32_e32 v57, v0
	v_mov_b32_e32 v58, v0
	v_mov_b32_e32 v59, v0
	v_mov_b32_e32 v60, v0
	v_mov_b32_e32 v61, v0
	v_mov_b32_e32 v62, v0
	v_mov_b32_e32 v63, v0
	v_mov_b32_e32 v64, v0
	v_mov_b32_e32 v65, v0
	v_mov_b32_e32 v66, v0
	v_mov_b32_e32 v67, v0
	v_mov_b32_e32 v68, v0
	v_mov_b32_e32 v69, v0
	v_mov_b32_e32 v70, v0
	v_mov_b32_e32 v71, v0
	v_mov_b32_e32 v80, v0
	v_mov_b32_e32 v81, v0
	v_mov_b32_e32 v82, v0
	v_mov_b32_e32 v83, v0
	v_mov_b32_e32 v84, v0
	v_mov_b32_e32 v85, v0
	v_mov_b32_e32 v86, v0
	v_mov_b32_e32 v87, v0
	v_mov_b32_e32 v96, v0
	v_mov_b32_e32 v97, v0
	v_mov_b32_e32 v98, v0
	v_mov_b32_e32 v99, v0
	v_mov_b32_e32 v100, v0
	v_mov_b32_e32 v101, v0
	v_mov_b32_e32 v102, v0
	v_mov_b32_e32 v103, v0
	v_mov_b32_e32 v116, v0
	v_mov_b32_e32 v117, v0
	v_mov_b32_e32 v118, v0
	v_mov_b32_e32 v119, v0
	v_mov_b32_e32 v124, v0
	v_mov_b32_e32 v125, v0
	v_mov_b32_e32 v126, v0
	v_mov_b32_e32 v127, v0
	v_mov_b32_e32 v72, v0
	v_mov_b32_e32 v73, v0
	v_mov_b32_e32 v74, v0
	v_mov_b32_e32 v75, v0
	v_mov_b32_e32 v76, v0
	v_mov_b32_e32 v77, v0
	v_mov_b32_e32 v78, v0
	v_mov_b32_e32 v79, v0
	v_mov_b32_e32 v88, v0
	v_mov_b32_e32 v89, v0
	v_mov_b32_e32 v90, v0
	v_mov_b32_e32 v91, v0
	v_mov_b32_e32 v92, v0
	v_mov_b32_e32 v93, v0
	v_mov_b32_e32 v94, v0
	v_mov_b32_e32 v95, v0
	v_mov_b32_e32 v104, v0
	v_mov_b32_e32 v105, v0
	v_mov_b32_e32 v106, v0
	v_mov_b32_e32 v107, v0
	v_mov_b32_e32 v112, v0
	v_mov_b32_e32 v113, v0
	v_mov_b32_e32 v114, v0
	v_mov_b32_e32 v115, v0
	v_mov_b32_e32 v136, v0
	v_mov_b32_e32 v137, v0
	v_mov_b32_e32 v138, v0
	v_mov_b32_e32 v139, v0
	v_mov_b32_e32 v144, v0
	v_mov_b32_e32 v145, v0
	v_mov_b32_e32 v146, v0
	v_mov_b32_e32 v147, v0
	v_readfirstlane_b32 s98, v171
	s_nop 3
	s_lshr_b32 s98, s98, 6
	s_cmp_ge_u32 s98, 4
	s_cbranch_scc0 .Lprio_130
	s_setprio 1

; template <class Epi, bool SEQ>
; DEV void gemm_phase(PG8_LAS unsigned char* lds, const Gemm g, const Epi& E) {
;     ...
;     const bool has_next = next_unit<SEQ>(g, ui + 1, G, cblk, nxt);
;     const char* nA = has_next ? PG8_ABASE(nxt) : cA; const char* nB = has_next ? PG8_BBASE(nxt) : cB;
;     ...
;     if (!keep) {
; #pragma unroll
;       for (int a = 0; a < 2; ++a)
; #pragma unroll
;         for (int b = 0; b < 2; ++b)
; #pragma unroll
;           for (int m = 0; m < 4; ++m)
; #pragma unroll
;             for (int n = 0; n < 2; ++n) acc[a][b][m][n] = (f32x4){0.f, 0.f, 0.f, 0.f};
;     }
;     cur = nxt; cA = nA; cB = nB; ++ui;
.LBB0_286:
	s_ashr_i32 s13, s12, 31
	s_lshl_b64 s[16:17], s[12:13], 19
	s_add_u32 s16, s24, s16
	s_addc_u32 s17, s25, s17
	s_and_b64 s[18:19], s[8:9], exec
	s_cselect_b32 s13, s17, s21
	s_cselect_b32 s49, s16, s20
	s_ashr_i32 s15, s14, 31
	s_lshl_b64 s[18:19], s[14:15], 19
	s_add_u32 s18, s0, s18
	s_addc_u32 s19, s1, s19
	s_and_b64 s[36:37], s[8:9], exec
	s_cselect_b32 s15, s19, s27
	s_cselect_b32 s50, s18, s26
	s_add_u32 s20, s20, 0x40080
	s_addc_u32 s21, s21, 0
	s_add_u32 s51, s26, 0x100
	v_mov_b64_e32 v[0:1], 0
	v_mov_b64_e32 v[2:3], 0
	v_mov_b64_e32 v[4:5], 0
	v_mov_b64_e32 v[6:7], 0
	v_mov_b64_e32 v[8:9], 0
	v_mov_b64_e32 v[10:11], 0
	v_mov_b64_e32 v[12:13], 0
	v_mov_b64_e32 v[14:15], 0
	v_mov_b64_e32 v[16:17], 0
	v_mov_b64_e32 v[18:19], 0
	v_mov_b64_e32 v[20:21], 0
	v_mov_b64_e32 v[22:23], 0
	v_mov_b64_e32 v[24:25], 0
	v_mov_b64_e32 v[26:27], 0
	v_mov_b64_e32 v[28:29], 0
	v_mov_b64_e32 v[30:31], 0
	v_mov_b64_e32 v[32:33], 0
	v_mov_b64_e32 v[34:35], 0
	v_mov_b64_e32 v[36:37], 0
	v_mov_b64_e32 v[38:39], 0
	v_mov_b64_e32 v[40:41], 0
	v_mov_b64_e32 v[42:43], 0
	v_mov_b64_e32 v[44:45], 0
	v_mov_b64_e32 v[46:47], 0
	v_mov_b64_e32 v[48:49], 0
	v_mov_b64_e32 v[50:51], 0
	v_mov_b64_e32 v[52:53], 0
	v_mov_b64_e32 v[54:55], 0
	v_mov_b64_e32 v[56:57], 0
	v_mov_b64_e32 v[58:59], 0
	v_mov_b64_e32 v[60:61], 0
	v_mov_b64_e32 v[62:63], 0
	v_mov_b64_e32 v[64:65], 0
	v_mov_b64_e32 v[66:67], 0
	v_mov_b64_e32 v[68:69], 0
	v_mov_b64_e32 v[70:71], 0
	v_mov_b64_e32 v[72:73], 0
	v_mov_b64_e32 v[74:75], 0
	v_mov_b64_e32 v[76:77], 0
	v_mov_b64_e32 v[78:79], 0
	v_mov_b64_e32 v[80:81], 0
	v_mov_b64_e32 v[82:83], 0
	v_mov_b64_e32 v[84:85], 0
	v_mov_b64_e32 v[86:87], 0
	v_mov_b64_e32 v[88:89], 0
	v_mov_b64_e32 v[90:91], 0
	v_mov_b64_e32 v[92:93], 0
	v_mov_b64_e32 v[94:95], 0
	v_mov_b64_e32 v[96:97], 0
	v_mov_b64_e32 v[98:99], 0
	v_mov_b64_e32 v[100:101], 0
	v_mov_b64_e32 v[102:103], 0
	v_mov_b64_e32 v[104:105], 0
	v_mov_b64_e32 v[106:107], 0
	v_mov_b64_e32 v[108:109], 0
	v_mov_b64_e32 v[110:111], 0
	v_mov_b64_e32 v[112:113], 0
	v_mov_b64_e32 v[114:115], 0
	v_mov_b64_e32 v[116:117], 0
	v_mov_b64_e32 v[118:119], 0
	v_mov_b64_e32 v[120:121], 0
	v_mov_b64_e32 v[122:123], 0
	v_mov_b64_e32 v[124:125], 0
	v_mov_b64_e32 v[126:127], 0
	s_addc_u32 s52, s27, 0
	s_mov_b32 s53, -2
	v_readfirstlane_b32 s98, v171
	s_nop 3
	s_lshr_b32 s98, s98, 6
	s_cmp_ge_u32 s98, 4
	s_cbranch_scc0 .Lprio_287
	s_setprio 1

; template <class Epi, bool SEQ>
; DEV void gemm_phase(PG8_LAS unsigned char* lds, const Gemm g, const Epi& E) {
;     ...
;     const bool has_next = next_unit<SEQ>(g, ui + 1, G, cblk, nxt);
;     const char* nA = has_next ? PG8_ABASE(nxt) : cA; const char* nB = has_next ? PG8_BBASE(nxt) : cB;
.LBB0_316:
	s_ashr_i32 s13, s12, 31
	s_lshl_b64 s[16:17], s[12:13], 20
	s_add_u32 s13, s35, s16
	s_addc_u32 s26, s36, s17
	s_ashr_i32 s9, s8, 31
	s_lshl_b64 s[16:17], s[8:9], 18
	s_add_u32 s16, s13, s16
	s_addc_u32 s17, s26, s17
	s_and_b64 s[0:1], s[0:1], exec
	s_cselect_b32 s9, s17, s21
	s_cselect_b32 s13, s16, s20
	s_add_u32 s51, s20, 0x100
	s_addc_u32 s52, s21, 0
	s_mov_b32 s53, -2
	v_readfirstlane_b32 s98, v171
	s_nop 3
	s_lshr_b32 s98, s98, 6
	s_cmp_ge_u32 s98, 4
	s_cbranch_scc0 .Lprio_317
	s_setprio 1
